# DIFF attention: V fragments loaded once for both maps and prefetched after QK; K fragment reads batched
# speedup vs baseline: 1.0023x; 1.0023x over previous
; DI float ex2(float x) { return __builtin_amdgcn_exp2f(x); }
; template <int MM> DI void smax_step(const f32x16& s, unsigned vm, float& m, float& l, f32x16 (&o)[2], bf16x8 (&pf)[2], int lane) {
;     float t[16], mx = -1e30f;
; #pragma unroll
;     for (int i = 0; i < 16; ++i) { t[i] = (MM == 0) ? s[i] : (MM == 1 ? (vm ? s[i] : -1e30f) : (((vm >> i) & 1u) ? s[i] : -1e30f)); mx = fmaxf(mx, t[i]); }
;     mx = fmaxf(mx, shx32(mx, lane));
;     const float mn = (mx > m + 8.0f) ? mx : m;
;     const float mref = fmaxf(mn, -1e29f);
;     float p[16], rs = 0.f;
; #pragma unroll
;     for (int i = 0; i < 16; ++i) { p[i] = ex2(t[i] - mref); rs += p[i]; }
;     rs += shx32(rs, lane);
;     if (__builtin_amdgcn_ballot_w64(mn != m) != 0ull) {
;         const float alpha = ex2(m - mn);
;         l *= alpha;
; #pragma unroll
;         for (int i = 0; i < 16; ++i) { o[0][i] *= alpha; o[1][i] *= alpha; }
;         m = mn;
;     }
;     l += rs;
;     pack_p(p, pf);
; }
; template <int MODE, bool PRE = false> ...
;     ...
;             if (MODE == MODE_DIFF) {
;                 const f32x16 s1 = qk_rows<0, 2>(Kl, 32 * sub, qf, r, h), s2 = qk_rows<2, 4>(Kl, 32 * sub, qf, r, h);
;                 bf16x8 pf2[2];
;                 if (mm == 0) { smax_step<0>(s1, vm, m1, l1, o1, pf, lane); smax_step<0>(s2, vm, m2, l2, o2, pf2, lane); }
;                 else { smax_step<2>(s1, vm, m1, l1, o1, pf, lane); smax_step<2>(s2, vm, m2, l2, o2, pf2, lane); }
.LBB0_791:
	s_andn2_b64 vcc, exec, s[38:39]
	s_cbranch_vccnz .LBB0_804
	v_add_u32_e32 v33, v227, v221
	ds_read_b128 v[34:37], v33
	ds_read_b128 v[38:41], v33 offset:32
	ds_read_b128 v[52:55], v33 offset:64
	ds_read_b128 v[56:59], v33 offset:96
	s_setprio 1
	s_waitcnt lgkmcnt(3)
	v_mfma_f32_32x32x16_bf16 v[112:127], v[34:37], v[152:155], 0
	s_waitcnt lgkmcnt(2)
	v_mfma_f32_32x32x16_bf16 v[112:127], v[38:41], v[156:159], v[112:127]
	s_waitcnt lgkmcnt(1)
	v_mfma_f32_32x32x16_bf16 v[96:111], v[52:55], v[160:163], 0
	s_waitcnt lgkmcnt(0)
	v_mfma_f32_32x32x16_bf16 v[96:111], v[56:59], v[164:167], v[96:111]
	s_setprio 0
	v_add_u32_e32 v51, v225, v222
	ds_read_b64_tr_b16 v[52:53], v51 offset:9216
	ds_read_b64_tr_b16 v[54:55], v51 offset:10368
	ds_read_b64_tr_b16 v[56:57], v51 offset:9280
	ds_read_b64_tr_b16 v[58:59], v51 offset:10432
	ds_read_b64_tr_b16 v[60:61], v51 offset:11520
	ds_read_b64_tr_b16 v[62:63], v51 offset:12672
	s_andn2_b64 vcc, exec, s[0:1]
	v_add_f32_e32 v229, 0x41000000, v226
	s_cbranch_vccz .LBB0_796
	v_and_b32_e32 v33, 1, v32
	v_and_b32_e32 v34, 2, v32
	v_cmp_eq_u32_e64 s[0:1], 0, v33
	v_cmp_eq_u32_e64 s[38:39], 0, v34
	v_and_b32_e32 v36, 4, v32
	v_and_b32_e32 v37, 8, v32
	v_cndmask_b32_e64 v33, v112, v208, s[0:1]
	v_cndmask_b32_e64 v34, v113, v208, s[38:39]
	v_cmp_eq_u32_e64 s[40:41], 0, v36
	v_cmp_eq_u32_e64 s[42:43], 0, v37
	v_and_b32_e32 v38, 16, v32
	v_and_b32_e32 v39, 32, v32
	v_max3_f32 v35, v33, s15, v34
	v_cndmask_b32_e64 v36, v114, v208, s[40:41]
	v_cndmask_b32_e64 v37, v115, v208, s[42:43]
	v_cmp_eq_u32_e64 s[44:45], 0, v38
	v_cmp_eq_u32_e64 s[48:49], 0, v39
	v_and_b32_e32 v40, 64, v32
	v_and_b32_e32 v41, 0x80, v32
	v_max3_f32 v35, v35, v36, v37
	v_cndmask_b32_e64 v38, v116, v208, s[44:45]
	v_cndmask_b32_e64 v39, v117, v208, s[48:49]
	v_cmp_eq_u32_e64 s[50:51], 0, v40
	v_cmp_eq_u32_e64 s[52:53], 0, v41
	v_and_b32_e32 v42, 0x100, v32
	v_and_b32_e32 v43, 0x200, v32
	v_max3_f32 v35, v35, v38, v39
	v_cndmask_b32_e64 v40, v118, v208, s[50:51]
	v_cndmask_b32_e64 v41, v119, v208, s[52:53]
	v_cmp_eq_u32_e64 s[54:55], 0, v42
	v_cmp_eq_u32_e64 s[56:57], 0, v43
	v_and_b32_e32 v44, 0x400, v32
	v_and_b32_e32 v45, 0x800, v32
	v_max3_f32 v35, v35, v40, v41
	v_cndmask_b32_e64 v42, v120, v208, s[54:55]
	v_cndmask_b32_e64 v43, v121, v208, s[56:57]
	v_cmp_eq_u32_e64 s[58:59], 0, v44
	v_cmp_eq_u32_e64 s[60:61], 0, v45
	v_and_b32_e32 v46, 0x1000, v32
	v_and_b32_e32 v47, 0x2000, v32
	v_max3_f32 v35, v35, v42, v43
	v_cndmask_b32_e64 v44, v122, v208, s[58:59]
	v_cndmask_b32_e64 v45, v123, v208, s[60:61]
	v_cmp_eq_u32_e64 s[62:63], 0, v46
	v_cmp_eq_u32_e64 s[64:65], 0, v47
	v_and_b32_e32 v48, 0x4000, v32
	v_and_b32_e32 v32, 0x8000, v32
	v_max3_f32 v35, v35, v44, v45
	v_cndmask_b32_e64 v46, v124, v208, s[62:63]
	v_cndmask_b32_e64 v47, v125, v208, s[64:65]
	v_cmp_eq_u32_e64 s[66:67], 0, v48
	v_cmp_eq_u32_e64 s[68:69], 0, v32
	v_max3_f32 v35, v35, v46, v47
	v_cndmask_b32_e64 v48, v126, v208, s[66:67]
	v_cndmask_b32_e64 v32, v127, v208, s[68:69]
	v_max3_f32 v35, v35, v48, v32
	v_mov_b32_e32 v49, v35
	v_mov_b32_e32 v50, v35
	s_nop 1
	v_permlane32_swap_b32_e32 v49, v50
	v_max_f32_e32 v35, v49, v50
	v_cmp_gt_f32_e32 vcc, v35, v229
	v_mov_b32_e32 v228, v226
	v_mov_b32_e32 v192, v186
	v_cndmask_b32_e32 v130, v226, v35, vcc
	v_max_f32_e32 v35, 0xefa18f08, v130
	v_sub_f32_e32 v33, v33, v35
	v_exp_f32_e32 v128, v33
	v_sub_f32_e32 v33, v34, v35
	v_exp_f32_e32 v129, v33
	v_sub_f32_e32 v33, v36, v35
	v_exp_f32_e32 v131, v33
	v_sub_f32_e32 v33, v37, v35
	v_exp_f32_e32 v132, v33
	v_sub_f32_e32 v34, v38, v35
	v_exp_f32_e32 v133, v34
	v_sub_f32_e32 v34, v39, v35
	v_add_f32_e32 v33, v129, v128
	v_exp_f32_e32 v134, v34
	v_sub_f32_e32 v34, v40, v35
	v_add_f32_e32 v33, v131, v33
	v_exp_f32_e32 v135, v34
	v_sub_f32_e32 v34, v41, v35
	v_add_f32_e32 v33, v132, v33
	v_exp_f32_e32 v187, v34
	v_sub_f32_e32 v34, v42, v35
	v_add_f32_e32 v33, v133, v33
	v_exp_f32_e32 v189, v34
	v_sub_f32_e32 v34, v43, v35
	v_add_f32_e32 v33, v134, v33
	v_exp_f32_e32 v190, v34
	v_sub_f32_e32 v34, v44, v35
	v_add_f32_e32 v33, v135, v33
	v_exp_f32_e32 v191, v34
	v_sub_f32_e32 v34, v45, v35
	v_add_f32_e32 v33, v187, v33
	v_exp_f32_e32 v193, v34
	v_sub_f32_e32 v34, v46, v35
	v_add_f32_e32 v33, v189, v33
	v_exp_f32_e32 v230, v34
	v_sub_f32_e32 v34, v47, v35
	v_add_f32_e32 v33, v190, v33
	v_exp_f32_e32 v231, v34
	v_sub_f32_e32 v34, v48, v35
	v_add_f32_e32 v33, v191, v33
	v_exp_f32_e32 v232, v34
	v_sub_f32_e32 v32, v32, v35
	v_add_f32_e32 v33, v193, v33
	v_exp_f32_e32 v233, v32
	v_add_f32_e32 v32, v230, v33
	v_add_f32_e32 v32, v231, v32
	v_add_f32_e32 v32, v232, v32
	v_add_f32_e32 v188, v233, v32
	v_mov_b32_e32 v234, v188
	v_mov_b32_e32 v235, v188
	s_nop 0
	s_nop 0
	v_permlane32_swap_b32_e32 v234, v235
	v_cmp_neq_f32_e32 vcc, v130, v226
	s_cbranch_vccz .LBB0_795
	v_sub_f32_e32 v32, v226, v130
	v_exp_f32_e32 v32, v32
	v_mov_b32_e32 v228, v130
	v_mul_f32_e32 v192, v186, v32
	v_pk_mul_f32 v[30:31], v[30:31], v[32:33] op_sel_hi:[1,0]
	v_pk_mul_f32 v[28:29], v[28:29], v[32:33] op_sel_hi:[1,0]
	v_pk_mul_f32 v[26:27], v[26:27], v[32:33] op_sel_hi:[1,0]
	v_pk_mul_f32 v[24:25], v[24:25], v[32:33] op_sel_hi:[1,0]
	v_pk_mul_f32 v[22:23], v[22:23], v[32:33] op_sel_hi:[1,0]
	v_pk_mul_f32 v[20:21], v[20:21], v[32:33] op_sel_hi:[1,0]
	v_pk_mul_f32 v[18:19], v[18:19], v[32:33] op_sel_hi:[1,0]
	v_pk_mul_f32 v[16:17], v[16:17], v[32:33] op_sel_hi:[1,0]
	v_pk_mul_f32 v[14:15], v[14:15], v[32:33] op_sel_hi:[1,0]
	v_pk_mul_f32 v[12:13], v[12:13], v[32:33] op_sel_hi:[1,0]
	v_pk_mul_f32 v[10:11], v[10:11], v[32:33] op_sel_hi:[1,0]
	v_pk_mul_f32 v[8:9], v[8:9], v[32:33] op_sel_hi:[1,0]
	v_pk_mul_f32 v[6:7], v[6:7], v[32:33] op_sel_hi:[1,0]
	v_pk_mul_f32 v[4:5], v[4:5], v[32:33] op_sel_hi:[1,0]
	v_pk_mul_f32 v[2:3], v[2:3], v[32:33] op_sel_hi:[1,0]
	v_pk_mul_f32 v[0:1], v[0:1], v[32:33] op_sel_hi:[1,0]

; #define LAS __attribute__((address_space(3)))
; #define MFMA32(a, b, c) __builtin_amdgcn_mfma_f32_32x32x16_bf16((a), (b), (c), 0, 0, 0)
; DI s16x4 vtr(LAS const char* p) { return __builtin_bit_cast(s16x4, __builtin_amdgcn_ds_read_tr16_b64_v4i16((LAS v4i16_t*)p)); }
; DI void pv_rows(f32x16 (&o)[2], LAS const char* Vl, int row0, const bf16x8 (&pf)[2], int lane) {
;     const int h = lane >> 5, i = lane & 15, grp = (lane >> 4) & 1;
;     LAS const char* base = Vl + (row0 + 4 * h + (i >> 2)) * KP + grp * 32 + (i & 3) * 8;
;     bf16x8 vf[2][2];
; #pragma unroll
;     for (int dt = 0; dt < 2; ++dt)
; #pragma unroll
;         for (int s2 = 0; s2 < 2; ++s2) {
;             const s16x4 lo = vtr(base + (16 * s2) * KP + dt * 64), hi = vtr(base + (16 * s2 + 8) * KP + dt * 64);
;             vf[dt][s2] = (bf16x8){lo[0], lo[1], lo[2], lo[3], hi[0], hi[1], hi[2], hi[3]};
;         }
;     __builtin_amdgcn_s_setprio(1);
; #pragma unroll
;     for (int s2 = 0; s2 < 2; ++s2)
; #pragma unroll
;         for (int dt = 0; dt < 2; ++dt) o[dt] = MFMA32(vf[dt][s2], pf[s2], o[dt]);
;     __builtin_amdgcn_s_setprio(0);
; template <int MODE, bool PRE = false> ...
;     ...
;                 pv_rows(o1, Vl, 32 * sub, pf, lane);
;                 pv_rows(o2, Vl, 32 * sub, pf2, lane);
.LBB0_803:
	ds_read_b64_tr_b16 v[44:45], v51 offset:11584
	ds_read_b64_tr_b16 v[46:47], v51 offset:12736
	v_cndmask_b32_e64 v32, v188, v192, s[36:37]
	v_add_f32_e32 v32, v191, v32
	v_add_f32_e32 v217, v217, v32
	v_cvt_pk_bf16_f32 v32, v231, v232
	v_cvt_pk_bf16_f32 v33, v233, v234
	v_cvt_pk_bf16_f32 v34, v235, v236
	v_cvt_pk_bf16_f32 v35, v237, v238
	v_cvt_pk_bf16_f32 v36, v239, v240
	v_cvt_pk_bf16_f32 v37, v241, v242
	v_cvt_pk_bf16_f32 v38, v243, v244
	v_cvt_pk_bf16_f32 v39, v189, v187
	s_setprio 1
	s_waitcnt lgkmcnt(2)
	v_mfma_f32_32x32x16_bf16 v[0:15], v[52:55], v[128:131], v[0:15]
	v_mfma_f32_32x32x16_bf16 v[16:31], v[56:59], v[128:131], v[16:31]
	v_mfma_f32_32x32x16_bf16 v[0:15], v[60:63], v[132:135], v[0:15]
	s_waitcnt lgkmcnt(0)
	v_mfma_f32_32x32x16_bf16 v[16:31], v[44:47], v[132:135], v[16:31]
	v_mfma_f32_32x32x16_bf16 v[64:79], v[52:55], v[32:35], v[64:79]
	v_mfma_f32_32x32x16_bf16 v[80:95], v[56:59], v[32:35], v[80:95]
	v_mfma_f32_32x32x16_bf16 v[64:79], v[60:63], v[36:39], v[64:79]
	v_mfma_f32_32x32x16_bf16 v[80:95], v[44:47], v[36:39], v[80:95]
	s_setprio 0
	v_mov_b32_e32 v186, v190
	v_mov_b32_e32 v226, v228

; DI float ex2(float x) { return __builtin_amdgcn_exp2f(x); }
; template <int MM> DI void smax_step(const f32x16& s, unsigned vm, float& m, float& l, f32x16 (&o)[2], bf16x8 (&pf)[2], int lane) {
;     float t[16], mx = -1e30f;
; #pragma unroll
;     for (int i = 0; i < 16; ++i) { t[i] = (MM == 0) ? s[i] : (MM == 1 ? (vm ? s[i] : -1e30f) : (((vm >> i) & 1u) ? s[i] : -1e30f)); mx = fmaxf(mx, t[i]); }
;     mx = fmaxf(mx, shx32(mx, lane));
;     const float mn = (mx > m + 8.0f) ? mx : m;
;     const float mref = fmaxf(mn, -1e29f);
;     float p[16], rs = 0.f;
; #pragma unroll
;     for (int i = 0; i < 16; ++i) { p[i] = ex2(t[i] - mref); rs += p[i]; }
;     rs += shx32(rs, lane);
;     if (__builtin_amdgcn_ballot_w64(mn != m) != 0ull) {
;         const float alpha = ex2(m - mn);
;         l *= alpha;
; #pragma unroll
;         for (int i = 0; i < 16; ++i) { o[0][i] *= alpha; o[1][i] *= alpha; }
;         m = mn;
;     }
;     l += rs;
;     pack_p(p, pf);
; }
; template <int MODE, bool PRE = false> ...
;     ...
;             if (MODE == MODE_DIFF) {
;                 const f32x16 s1 = qk_rows<0, 2>(Kl, 32 * sub, qf, r, h), s2 = qk_rows<2, 4>(Kl, 32 * sub, qf, r, h);
;                 bf16x8 pf2[2];
;                 if (mm == 0) { smax_step<0>(s1, vm, m1, l1, o1, pf, lane); smax_step<0>(s2, vm, m2, l2, o2, pf2, lane); }
;                 else { smax_step<2>(s1, vm, m1, l1, o1, pf, lane); smax_step<2>(s2, vm, m2, l2, o2, pf2, lane); }
.LBB0_810:
	s_andn2_b64 vcc, exec, s[38:39]
	s_cbranch_vccnz .LBB0_823
	v_add_u32_e32 v33, v227, v223
	ds_read_b128 v[34:37], v33
	ds_read_b128 v[38:41], v33 offset:32
	ds_read_b128 v[52:55], v33 offset:64
	ds_read_b128 v[56:59], v33 offset:96
	s_setprio 1
	s_waitcnt lgkmcnt(3)
	v_mfma_f32_32x32x16_bf16 v[112:127], v[34:37], v[152:155], 0
	s_waitcnt lgkmcnt(2)
	v_mfma_f32_32x32x16_bf16 v[112:127], v[38:41], v[156:159], v[112:127]
	s_waitcnt lgkmcnt(1)
	v_mfma_f32_32x32x16_bf16 v[96:111], v[52:55], v[160:163], 0
	s_waitcnt lgkmcnt(0)
	v_mfma_f32_32x32x16_bf16 v[96:111], v[56:59], v[164:167], v[96:111]
	s_setprio 0
	v_add_u32_e32 v51, v225, v222
	ds_read_b64_tr_b16 v[52:53], v51 offset:13824
	ds_read_b64_tr_b16 v[54:55], v51 offset:14976
	ds_read_b64_tr_b16 v[56:57], v51 offset:13888
	ds_read_b64_tr_b16 v[58:59], v51 offset:15040
	ds_read_b64_tr_b16 v[60:61], v51 offset:16128
	ds_read_b64_tr_b16 v[62:63], v51 offset:17280
	s_and_b64 vcc, exec, s[0:1]
	v_add_f32_e32 v187, 0x41000000, v226
	s_cbranch_vccnz .LBB0_815
	v_and_b32_e32 v33, 1, v32
	v_and_b32_e32 v34, 2, v32
	v_cmp_eq_u32_e64 s[0:1], 0, v33
	v_cmp_eq_u32_e64 s[38:39], 0, v34
	v_and_b32_e32 v36, 4, v32
	v_and_b32_e32 v37, 8, v32
	v_cndmask_b32_e64 v33, v112, v208, s[0:1]
	v_cndmask_b32_e64 v34, v113, v208, s[38:39]
	v_cmp_eq_u32_e64 s[40:41], 0, v36
	v_cmp_eq_u32_e64 s[42:43], 0, v37
	v_and_b32_e32 v38, 16, v32
	v_and_b32_e32 v39, 32, v32
	v_max3_f32 v35, v33, s15, v34
	v_cndmask_b32_e64 v36, v114, v208, s[40:41]
	v_cndmask_b32_e64 v37, v115, v208, s[42:43]
	v_cmp_eq_u32_e64 s[44:45], 0, v38
	v_cmp_eq_u32_e64 s[48:49], 0, v39
	v_and_b32_e32 v40, 64, v32
	v_and_b32_e32 v41, 0x80, v32
	v_max3_f32 v35, v35, v36, v37
	v_cndmask_b32_e64 v38, v116, v208, s[44:45]
	v_cndmask_b32_e64 v39, v117, v208, s[48:49]
	v_cmp_eq_u32_e64 s[50:51], 0, v40
	v_cmp_eq_u32_e64 s[52:53], 0, v41
	v_and_b32_e32 v42, 0x100, v32
	v_and_b32_e32 v43, 0x200, v32
	v_max3_f32 v35, v35, v38, v39
	v_cndmask_b32_e64 v40, v118, v208, s[50:51]
	v_cndmask_b32_e64 v41, v119, v208, s[52:53]
	v_cmp_eq_u32_e64 s[54:55], 0, v42
	v_cmp_eq_u32_e64 s[56:57], 0, v43
	v_and_b32_e32 v44, 0x400, v32
	v_and_b32_e32 v45, 0x800, v32
	v_max3_f32 v35, v35, v40, v41
	v_cndmask_b32_e64 v42, v120, v208, s[54:55]
	v_cndmask_b32_e64 v43, v121, v208, s[56:57]
	v_cmp_eq_u32_e64 s[58:59], 0, v44
	v_cmp_eq_u32_e64 s[60:61], 0, v45
	v_and_b32_e32 v46, 0x1000, v32
	v_and_b32_e32 v47, 0x2000, v32
	v_max3_f32 v35, v35, v42, v43
	v_cndmask_b32_e64 v44, v122, v208, s[58:59]
	v_cndmask_b32_e64 v45, v123, v208, s[60:61]
	v_cmp_eq_u32_e64 s[62:63], 0, v46
	v_cmp_eq_u32_e64 s[64:65], 0, v47
	v_and_b32_e32 v48, 0x4000, v32
	v_and_b32_e32 v32, 0x8000, v32
	v_max3_f32 v35, v35, v44, v45
	v_cndmask_b32_e64 v46, v124, v208, s[62:63]
	v_cndmask_b32_e64 v47, v125, v208, s[64:65]
	v_cmp_eq_u32_e64 s[66:67], 0, v48
	v_cmp_eq_u32_e64 s[68:69], 0, v32
	v_max3_f32 v35, v35, v46, v47
	v_cndmask_b32_e64 v48, v126, v208, s[66:67]
	v_cndmask_b32_e64 v32, v127, v208, s[68:69]
	v_max3_f32 v35, v35, v48, v32
	v_mov_b32_e32 v49, v35
	v_mov_b32_e32 v50, v35
	s_nop 1
	v_permlane32_swap_b32_e32 v49, v50
	v_max_f32_e32 v35, v49, v50
	v_cmp_gt_f32_e32 vcc, v35, v187
	v_mov_b32_e32 v227, v226
	v_mov_b32_e32 v192, v186
	v_cndmask_b32_e32 v130, v226, v35, vcc
	v_max_f32_e32 v35, 0xefa18f08, v130
	v_sub_f32_e32 v33, v33, v35
	v_exp_f32_e32 v128, v33
	v_sub_f32_e32 v33, v34, v35
	v_exp_f32_e32 v129, v33
	v_sub_f32_e32 v33, v36, v35
	v_exp_f32_e32 v131, v33
	v_sub_f32_e32 v33, v37, v35
	v_exp_f32_e32 v132, v33
	v_sub_f32_e32 v34, v38, v35
	v_exp_f32_e32 v133, v34
	v_sub_f32_e32 v34, v39, v35
	v_add_f32_e32 v33, v129, v128
	v_exp_f32_e32 v134, v34
	v_sub_f32_e32 v34, v40, v35
	v_add_f32_e32 v33, v131, v33
	v_exp_f32_e32 v135, v34
	v_sub_f32_e32 v34, v41, v35
	v_add_f32_e32 v33, v132, v33
	v_exp_f32_e32 v189, v34
	v_sub_f32_e32 v34, v42, v35
	v_add_f32_e32 v33, v133, v33
	v_exp_f32_e32 v190, v34
	v_sub_f32_e32 v34, v43, v35
	v_add_f32_e32 v33, v134, v33
	v_exp_f32_e32 v191, v34
	v_sub_f32_e32 v34, v44, v35
	v_add_f32_e32 v33, v135, v33
	v_exp_f32_e32 v193, v34
	v_sub_f32_e32 v34, v45, v35
	v_add_f32_e32 v33, v189, v33
	v_exp_f32_e32 v228, v34
	v_sub_f32_e32 v34, v46, v35
	v_add_f32_e32 v33, v190, v33
	v_exp_f32_e32 v229, v34
	v_sub_f32_e32 v34, v47, v35
	v_add_f32_e32 v33, v191, v33
	v_exp_f32_e32 v230, v34
	v_sub_f32_e32 v34, v48, v35
	v_add_f32_e32 v33, v193, v33
	v_exp_f32_e32 v231, v34
	v_sub_f32_e32 v32, v32, v35
	v_add_f32_e32 v33, v228, v33
	v_exp_f32_e32 v232, v32
	v_add_f32_e32 v32, v229, v33
	v_add_f32_e32 v32, v230, v32
	v_add_f32_e32 v32, v231, v32
	v_add_f32_e32 v188, v232, v32
	v_mov_b32_e32 v233, v188
	v_mov_b32_e32 v234, v188
	s_nop 0
	s_nop 0
	v_permlane32_swap_b32_e32 v233, v234
	v_cmp_neq_f32_e32 vcc, v130, v226
	s_cbranch_vccz .LBB0_814
	v_sub_f32_e32 v32, v226, v130
	v_exp_f32_e32 v32, v32
	v_mov_b32_e32 v227, v130
	v_mul_f32_e32 v192, v186, v32
	v_pk_mul_f32 v[30:31], v[30:31], v[32:33] op_sel_hi:[1,0]
	v_pk_mul_f32 v[28:29], v[28:29], v[32:33] op_sel_hi:[1,0]
	v_pk_mul_f32 v[26:27], v[26:27], v[32:33] op_sel_hi:[1,0]
	v_pk_mul_f32 v[24:25], v[24:25], v[32:33] op_sel_hi:[1,0]
	v_pk_mul_f32 v[22:23], v[22:23], v[32:33] op_sel_hi:[1,0]
	v_pk_mul_f32 v[20:21], v[20:21], v[32:33] op_sel_hi:[1,0]
	v_pk_mul_f32 v[18:19], v[18:19], v[32:33] op_sel_hi:[1,0]
	v_pk_mul_f32 v[16:17], v[16:17], v[32:33] op_sel_hi:[1,0]
	v_pk_mul_f32 v[14:15], v[14:15], v[32:33] op_sel_hi:[1,0]
	v_pk_mul_f32 v[12:13], v[12:13], v[32:33] op_sel_hi:[1,0]
	v_pk_mul_f32 v[10:11], v[10:11], v[32:33] op_sel_hi:[1,0]
	v_pk_mul_f32 v[8:9], v[8:9], v[32:33] op_sel_hi:[1,0]
	v_pk_mul_f32 v[6:7], v[6:7], v[32:33] op_sel_hi:[1,0]
	v_pk_mul_f32 v[4:5], v[4:5], v[32:33] op_sel_hi:[1,0]
	v_pk_mul_f32 v[2:3], v[2:3], v[32:33] op_sel_hi:[1,0]
	v_pk_mul_f32 v[0:1], v[0:1], v[32:33] op_sel_hi:[1,0]

; #define LAS __attribute__((address_space(3)))
; #define MFMA32(a, b, c) __builtin_amdgcn_mfma_f32_32x32x16_bf16((a), (b), (c), 0, 0, 0)
; DI s16x4 vtr(LAS const char* p) { return __builtin_bit_cast(s16x4, __builtin_amdgcn_ds_read_tr16_b64_v4i16((LAS v4i16_t*)p)); }
; DI void pv_rows(f32x16 (&o)[2], LAS const char* Vl, int row0, const bf16x8 (&pf)[2], int lane) {
;     const int h = lane >> 5, i = lane & 15, grp = (lane >> 4) & 1;
;     LAS const char* base = Vl + (row0 + 4 * h + (i >> 2)) * KP + grp * 32 + (i & 3) * 8;
;     bf16x8 vf[2][2];
; #pragma unroll
;     for (int dt = 0; dt < 2; ++dt)
; #pragma unroll
;         for (int s2 = 0; s2 < 2; ++s2) {
;             const s16x4 lo = vtr(base + (16 * s2) * KP + dt * 64), hi = vtr(base + (16 * s2 + 8) * KP + dt * 64);
;             vf[dt][s2] = (bf16x8){lo[0], lo[1], lo[2], lo[3], hi[0], hi[1], hi[2], hi[3]};
;         }
;     __builtin_amdgcn_s_setprio(1);
; #pragma unroll
;     for (int s2 = 0; s2 < 2; ++s2)
; #pragma unroll
;         for (int dt = 0; dt < 2; ++dt) o[dt] = MFMA32(vf[dt][s2], pf[s2], o[dt]);
;     __builtin_amdgcn_s_setprio(0);
; template <int MODE, bool PRE = false> ...
;     ...
;                 pv_rows(o1, Vl, 32 * sub, pf, lane);
;                 pv_rows(o2, Vl, 32 * sub, pf2, lane);
.LBB0_822:
	ds_read_b64_tr_b16 v[44:45], v51 offset:16192
	ds_read_b64_tr_b16 v[46:47], v51 offset:17344
	v_cndmask_b32_e64 v32, v188, v192, s[36:37]
	v_add_f32_e32 v32, v191, v32
	v_add_f32_e32 v217, v217, v32
	v_cvt_pk_bf16_f32 v32, v229, v230
	v_cvt_pk_bf16_f32 v33, v231, v232
	v_cvt_pk_bf16_f32 v34, v233, v234
	v_cvt_pk_bf16_f32 v35, v235, v236
	v_cvt_pk_bf16_f32 v36, v237, v238
	v_cvt_pk_bf16_f32 v37, v239, v240
	v_cvt_pk_bf16_f32 v38, v241, v242
	v_cvt_pk_bf16_f32 v39, v189, v193
	s_setprio 1
	s_waitcnt lgkmcnt(2)
	v_mfma_f32_32x32x16_bf16 v[0:15], v[52:55], v[128:131], v[0:15]
	v_mfma_f32_32x32x16_bf16 v[16:31], v[56:59], v[128:131], v[16:31]
	v_mfma_f32_32x32x16_bf16 v[0:15], v[60:63], v[132:135], v[0:15]
	s_waitcnt lgkmcnt(0)
	v_mfma_f32_32x32x16_bf16 v[16:31], v[44:47], v[132:135], v[16:31]
	v_mfma_f32_32x32x16_bf16 v[64:79], v[52:55], v[32:35], v[64:79]
	v_mfma_f32_32x32x16_bf16 v[80:95], v[56:59], v[32:35], v[80:95]
	v_mfma_f32_32x32x16_bf16 v[64:79], v[60:63], v[36:39], v[64:79]
	v_mfma_f32_32x32x16_bf16 v[80:95], v[44:47], v[36:39], v[80:95]
	s_setprio 0
	v_mov_b32_e32 v186, v190
	v_mov_b32_e32 v226, v227
